# EpiConv v5: one lane group reduces a whole PS row (16 partials) and an all-gather by two permlane swaps replaces 8 butterflies
# speedup vs baseline: 1.0033x; 1.0033x over previous
; template <class Epi, bool HALO>
; __device__ __forceinline__ void gemm_phase(LAS unsigned char* lds, const bf16_t* Ag, const bf16_t* Btg, const int K, const int nM, const int nN, const int G, const int cidx, const int wave_, const Epi& E) {
;     ...
;     f32x4 acc[2][2][4][2];
; #pragma unroll
;     for (int a = 0; a < 2; ++a)
; #pragma unroll
;         for (int b = 0; b < 2; ++b)
; #pragma unroll
;             for (int m = 0; m < 4; ++m)
; #pragma unroll
;                 for (int n = 0; n < 2; ++n) acc[a][b][m][n] = (f32x4){0.f, 0.f, 0.f, 0.f};
;     __device__ __forceinline__ void operator()(const f32x4 (&acc)[2][2][4][2], const Unit& u, int wr, int wc, int fr, int fq) const {
;         int seqbase, t0, slen; halo_decode(u.pm, seqbase, t0, slen);
;         const f32x4* ct = (const f32x4*)(CT + (size_t)(128 * u.pn) * 8) + (32 * wc + 8 * fq) * 2;
;         const bool f0 = (fr == 0), f15 = (fr == 15);
; #pragma unroll
;         for (int ai = 0; ai < 2; ++ai) {
;             const int tbase = t0 + 62 * (2 * ai + wr) - 1;
;             float rs[4];
; #pragma unroll
;             for (int m = 0; m < 4; ++m) { const int t = tbase + 16 * m + fr; const bool vin = (t >= 0) && (t < slen); const int grow = seqbase + (vin ? t : 0);
;                 const f32x4 p = *(const f32x4*)(PS + (size_t)grow * 16 + 4 * fq); float s = (p[0] + p[1]) + (p[2] + p[3]); s = bfly_add<16>(s); s = bfly_add<32>(s); rs[m] = vin ? rsqrtf(s * (1.f / DM) + EPS) : 0.f; }
EC2_join:
	s_mul_i32 s86, s86, 0xf8
	s_bfe_u32 s89, s81, 0x10008
	s_mul_i32 s89, s89, 62
	s_add_i32 s89, s89, s86
	s_add_i32 s89, s89, -1
	v_mbcnt_lo_u32_b32 v176, -1, 0
	v_mbcnt_hi_u32_b32 v176, -1, v176
	v_and_b32_e32 v164, 15, v176
	v_lshlrev_b32_e32 v164, 2, v164
	v_bfe_u32 v165, v176, 4, 2
	v_lshlrev_b32_e32 v172, 8, v165
	v_lshlrev_b32_e32 v165, 4, v165
	v_add_u32_e32 v174, s89, v164
	v_lshrrev_b32_e32 v176, 4, v165
	v_add_u32_e32 v176, v176, v174
	v_cmp_gt_u32_e32 vcc, s91, v176
	s_nop 1
	v_cndmask_b32_e32 v176, 0, v176, vcc
	v_add_u32_e32 v176, s88, v176
	v_lshlrev_b32_e32 v252, 6, v176
	global_load_dwordx4 v[240:243], v252, s[70:71]
	global_load_dwordx4 v[244:247], v252, s[70:71] offset:16
	global_load_dwordx4 v[248:251], v252, s[70:71] offset:32
	global_load_dwordx4 v[160:163], v252, s[70:71] offset:48
	s_ashr_i32 s29, s28, 31
	s_lshl_b64 s[20:21], s[28:29], 19
	s_add_u32 s34, s38, s20
	s_addc_u32 s35, s39, s21
	s_and_b64 s[14:15], s[14:15], exec
	s_cselect_b32 s20, s35, s19
	s_cselect_b32 s21, s34, s18
	s_add_u32 s2, s2, 0x3e080
	s_addc_u32 s3, s3, 0
	s_add_u32 s29, s18, 0x100
	v_mov_b32_e32 v0, 0
	s_addc_u32 s37, s19, 0
	s_mov_b32 s51, -2
	v_mov_b32_e32 v1, v0
	v_mov_b32_e32 v2, v0
	v_mov_b32_e32 v3, v0
	v_mov_b32_e32 v32, v0
	v_mov_b32_e32 v33, v0
	v_mov_b32_e32 v34, v0
	v_mov_b32_e32 v35, v0
	v_mov_b32_e32 v4, v0
	v_mov_b32_e32 v5, v0
	v_mov_b32_e32 v6, v0
	v_mov_b32_e32 v7, v0
	v_mov_b32_e32 v36, v0
	v_mov_b32_e32 v37, v0
	v_mov_b32_e32 v38, v0
	v_mov_b32_e32 v39, v0
	v_mov_b32_e32 v8, v0
	v_mov_b32_e32 v9, v0
	v_mov_b32_e32 v10, v0
	v_mov_b32_e32 v11, v0
	v_mov_b32_e32 v40, v0
	v_mov_b32_e32 v41, v0
	v_mov_b32_e32 v42, v0
	v_mov_b32_e32 v43, v0
	v_mov_b32_e32 v12, v0
	v_mov_b32_e32 v13, v0
	v_mov_b32_e32 v14, v0
	v_mov_b32_e32 v15, v0
	v_mov_b32_e32 v44, v0
	v_mov_b32_e32 v45, v0
	v_mov_b32_e32 v46, v0
	v_mov_b32_e32 v47, v0
	v_mov_b32_e32 v16, v0
	v_mov_b32_e32 v17, v0
	v_mov_b32_e32 v18, v0
	v_mov_b32_e32 v19, v0
	v_mov_b32_e32 v48, v0
	v_mov_b32_e32 v49, v0
	v_mov_b32_e32 v50, v0
	v_mov_b32_e32 v51, v0
	v_mov_b32_e32 v20, v0
	v_mov_b32_e32 v21, v0
	v_mov_b32_e32 v22, v0
	v_mov_b32_e32 v23, v0
	v_mov_b32_e32 v52, v0
	v_mov_b32_e32 v53, v0
	v_mov_b32_e32 v54, v0
	v_mov_b32_e32 v55, v0
	v_mov_b32_e32 v24, v0
	v_mov_b32_e32 v25, v0
	v_mov_b32_e32 v26, v0
	v_mov_b32_e32 v27, v0
	v_mov_b32_e32 v56, v0
	v_mov_b32_e32 v57, v0
	v_mov_b32_e32 v58, v0
	v_mov_b32_e32 v59, v0
	v_mov_b32_e32 v28, v0
	v_mov_b32_e32 v29, v0
	v_mov_b32_e32 v30, v0
	v_mov_b32_e32 v31, v0
	v_mov_b32_e32 v60, v0
	v_mov_b32_e32 v61, v0
	v_mov_b32_e32 v62, v0
	v_mov_b32_e32 v63, v0
	v_mov_b32_e32 v64, v0
	v_mov_b32_e32 v65, v0
	v_mov_b32_e32 v66, v0
	v_mov_b32_e32 v67, v0
	v_mov_b32_e32 v96, v0
	v_mov_b32_e32 v97, v0
	v_mov_b32_e32 v98, v0
	v_mov_b32_e32 v99, v0
	v_mov_b32_e32 v68, v0
	v_mov_b32_e32 v69, v0
	v_mov_b32_e32 v70, v0
	v_mov_b32_e32 v71, v0
	v_mov_b32_e32 v100, v0
	v_mov_b32_e32 v101, v0
	v_mov_b32_e32 v102, v0
	v_mov_b32_e32 v103, v0
	v_mov_b32_e32 v72, v0
	v_mov_b32_e32 v73, v0
	v_mov_b32_e32 v74, v0
	v_mov_b32_e32 v75, v0
	v_mov_b32_e32 v104, v0
	v_mov_b32_e32 v105, v0
	v_mov_b32_e32 v106, v0
	v_mov_b32_e32 v107, v0
	v_mov_b32_e32 v76, v0
	v_mov_b32_e32 v77, v0
	v_mov_b32_e32 v78, v0
	v_mov_b32_e32 v79, v0
	v_mov_b32_e32 v108, v0
	v_mov_b32_e32 v109, v0
	v_mov_b32_e32 v110, v0
	v_mov_b32_e32 v111, v0
	v_mov_b32_e32 v80, v0
	v_mov_b32_e32 v81, v0
	v_mov_b32_e32 v82, v0
	v_mov_b32_e32 v83, v0
	v_mov_b32_e32 v112, v0
	v_mov_b32_e32 v113, v0
	v_mov_b32_e32 v114, v0
	v_mov_b32_e32 v115, v0
	v_mov_b32_e32 v84, v0
	v_mov_b32_e32 v85, v0
	v_mov_b32_e32 v86, v0
	v_mov_b32_e32 v87, v0
	v_mov_b32_e32 v116, v0
	v_mov_b32_e32 v117, v0
	v_mov_b32_e32 v118, v0
	v_mov_b32_e32 v119, v0
	v_mov_b32_e32 v88, v0
	v_mov_b32_e32 v89, v0
	v_mov_b32_e32 v90, v0
	v_mov_b32_e32 v91, v0
	v_mov_b32_e32 v120, v0
	v_mov_b32_e32 v121, v0
	v_mov_b32_e32 v122, v0
	v_mov_b32_e32 v123, v0
	v_mov_b32_e32 v92, v0
	v_mov_b32_e32 v93, v0
	v_mov_b32_e32 v94, v0
	v_mov_b32_e32 v95, v0
	v_mov_b32_e32 v124, v0
	v_mov_b32_e32 v125, v0
	v_mov_b32_e32 v126, v0
	v_mov_b32_e32 v127, v0

; __device__ __forceinline__ float dpp_ror1(float x) { return __builtin_bit_cast(float, __builtin_amdgcn_mov_dpp(__builtin_bit_cast(int, x), 0x121, 0xF, 0xF, true)); }
;     __device__ __forceinline__ void operator()(const f32x4 (&acc)[2][2][4][2], const Unit& u, int wr, int wc, int fr, int fq) const {
;     ...
;             for (int m = 0; m < 4; ++m) { const int t = tbase + 16 * m + fr; const bool vin = (t >= 0) && (t < slen); const int grow = seqbase + (vin ? t : 0);
;                 const f32x4 p = *(const f32x4*)(PS + (size_t)grow * 16 + 4 * fq); float s = (p[0] + p[1]) + (p[2] + p[3]); s = bfly_add<16>(s); s = bfly_add<32>(s); rs[m] = vin ? rsqrtf(s * (1.f / DM) + EPS) : 0.f; }
;             unsigned outw[4][2][2];
; #pragma unroll
;             for (int n = 0; n < 2; ++n)
; #pragma unroll
;                 for (int jp = 0; jp < 2; ++jp) {
;                     const int cidx = (4 * n + 2 * jp) * 2;
;                     const f32x4 c0a = ct[cidx], c0b = ct[cidx + 1], c1a = ct[cidx + 2], c1b = ct[cidx + 3];
;                     const f32x2 wv0 = {c0a[0], c1a[0]}, wv1 = {c0a[1], c1a[1]}, wv2 = {c0a[2], c1a[2]}, bv = {c0a[3], c1a[3]};
;                     const f32x2 wg0 = {c0b[0], c1b[0]}, wg1 = {c0b[1], c1b[1]}, wg2 = {c0b[2], c1b[2]}, bg = {c0b[3], c1b[3]};
;                     f32x2 uv[4], ug[4], cv[4];
; #pragma unroll
;                     for (int m = 0; m < 4; ++m) { uv[m] = (f32x2){acc[ai][0][m][n][2 * jp], acc[ai][0][m][n][2 * jp + 1]}; ug[m] = (f32x2){acc[ai][1][m][n][2 * jp], acc[ai][1][m][n][2 * jp + 1]}; }
;                     asm volatile("" : "+v"(uv[0]), "+v"(uv[1]), "+v"(uv[2]), "+v"(uv[3]), "+v"(ug[0]), "+v"(ug[1]), "+v"(ug[2]), "+v"(ug[3]));
;                     {
;                         f32x2 rv[4], lv[4];
; #pragma unroll
;                         for (int m = 0; m < 4; ++m) { uv[m] = uv[m] * rs[m]; rv[m] = (f32x2){dpp_ror1(uv[m][0]), dpp_ror1(uv[m][1])}; lv[m] = (f32x2){dpp_ror15(uv[m][0]), dpp_ror15(uv[m][1])}; }
; #pragma unroll
;                         for (int m = 0; m < 4; ++m) { const f32x2 pv_ = (m > 0 && f0) ? rv[m > 0 ? m - 1 : 0] : rv[m], nv_ = (m < 3 && f15) ? lv[m < 3 ? m + 1 : 3] : lv[m];
;                             cv[m] = bv + wv0 * pv_ + wv1 * uv[m] + wv2 * nv_; }
.LBB0_790:
	s_lshl_b32 s92, s33, 12
	s_add_u32 s64, s100, s92
	s_addc_u32 s65, s101, 0
	s_lshl_b32 s92, s33, 8
	s_add_u32 s86, s98, s92
	s_addc_u32 s87, s99, 0
	v_mov_b32_e32 v252, s78
	s_movk_i32 s54, 0x1600
	global_load_dwordx4 v[190:193], v172, s[64:65]
	global_load_dwordx4 v[194:197], v172, s[64:65] offset:16
	global_load_dwordx4 v[198:201], v172, s[64:65] offset:32
	global_load_dwordx4 v[202:205], v172, s[64:65] offset:48
	v_lshrrev_b32_e32 v176, 4, v165
	v_add_u32_e32 v176, v176, v174
	v_cmp_gt_u32_e32 vcc, s91, v176
	s_waitcnt vmcnt(4)
	v_pk_add_f32 v[240:241], v[240:241], v[244:245]
	v_pk_add_f32 v[242:243], v[242:243], v[246:247]
	v_pk_add_f32 v[248:249], v[248:249], v[160:161]
	v_pk_add_f32 v[250:251], v[250:251], v[162:163]
	v_pk_add_f32 v[240:241], v[240:241], v[248:249]
	v_pk_add_f32 v[242:243], v[242:243], v[250:251]
	v_pk_add_f32 v[240:241], v[240:241], v[242:243]
	v_add_f32_e32 v240, v240, v241
	v_fma_f32 v240, v240, s82, v252
	v_rsq_f32_e32 v240, v240
	s_nop 0
	v_cndmask_b32_e32 v178, 0, v240, vcc
	v_mov_b32_e32 v180, v178
	s_nop 1
	v_permlane16_swap_b32_e32 v178, v180
	v_mov_b32_e32 v182, v178
	v_mov_b32_e32 v144, v180
	s_nop 1
	v_permlane32_swap_b32_e32 v178, v182
	v_permlane32_swap_b32_e32 v180, v144
	global_load_dwordx4 v[206:209], v172, s[64:65] offset:64
	global_load_dwordx4 v[210:213], v172, s[64:65] offset:80
	global_load_dwordx4 v[214:217], v172, s[64:65] offset:96
	global_load_dwordx4 v[218:221], v172, s[64:65] offset:112
	s_waitcnt vmcnt(4)
	v_pk_mul_f32 v[124:125], v[124:125], v[178:179] op_sel_hi:[1,0]
	v_pk_mul_f32 v[120:121], v[120:121], v[180:181] op_sel_hi:[1,0]
	v_pk_mul_f32 v[116:117], v[116:117], v[182:183] op_sel_hi:[1,0]
	v_pk_mul_f32 v[112:113], v[112:113], v[144:145] op_sel_hi:[1,0]
	v_pk_mul_f32 v[108:109], v[108:109], v[178:179] op_sel_hi:[1,0]
	v_pk_mul_f32 v[104:105], v[104:105], v[180:181] op_sel_hi:[1,0]
	v_pk_mul_f32 v[100:101], v[100:101], v[182:183] op_sel_hi:[1,0]
	v_pk_mul_f32 v[96:97], v[96:97], v[144:145] op_sel_hi:[1,0]
	s_nop 1
	v_mov_b32_dpp v248, v112 row_shr:1 row_mask:0xf bank_mask:0xf bound_ctrl:1
	v_mov_b32_dpp v249, v113 row_shr:1 row_mask:0xf bank_mask:0xf bound_ctrl:1
	v_mov_b32_dpp v250, v124 row_shl:1 row_mask:0xf bank_mask:0xf bound_ctrl:1
	v_mov_b32_dpp v251, v125 row_shl:1 row_mask:0xf bank_mask:0xf bound_ctrl:1
	v_pk_fma_f32 v[224:225], v[190:191], v[248:249], v[196:197]
	v_pk_fma_f32 v[226:227], v[190:191], v[124:125], v[196:197]
	v_pk_fma_f32 v[228:229], v[190:191], v[120:121], v[196:197]
	v_pk_fma_f32 v[230:231], v[190:191], v[116:117], v[196:197]
	v_pk_fma_f32 v[224:225], v[192:193], v[124:125], v[224:225]
	v_pk_fma_f32 v[226:227], v[192:193], v[120:121], v[226:227]
	v_pk_fma_f32 v[228:229], v[192:193], v[116:117], v[228:229]
	v_pk_fma_f32 v[230:231], v[192:193], v[112:113], v[230:231]
	v_pk_fma_f32 v[224:225], v[194:195], v[120:121], v[224:225]
	v_pk_fma_f32 v[226:227], v[194:195], v[116:117], v[226:227]
	v_pk_fma_f32 v[228:229], v[194:195], v[112:113], v[228:229]
	v_pk_fma_f32 v[230:231], v[194:195], v[250:251], v[230:231]
	s_nop 1
	v_mov_b32_dpp v248, v96 row_shr:1 row_mask:0xf bank_mask:0xf bound_ctrl:1
	v_mov_b32_dpp v249, v97 row_shr:1 row_mask:0xf bank_mask:0xf bound_ctrl:1
	v_mov_b32_dpp v250, v108 row_shl:1 row_mask:0xf bank_mask:0xf bound_ctrl:1
	v_mov_b32_dpp v251, v109 row_shl:1 row_mask:0xf bank_mask:0xf bound_ctrl:1
	v_pk_fma_f32 v[232:233], v[198:199], v[248:249], v[204:205]
	v_pk_fma_f32 v[234:235], v[198:199], v[108:109], v[204:205]
	v_pk_fma_f32 v[236:237], v[198:199], v[104:105], v[204:205]
	v_pk_fma_f32 v[238:239], v[198:199], v[100:101], v[204:205]
	v_pk_fma_f32 v[232:233], v[200:201], v[108:109], v[232:233]
	v_pk_fma_f32 v[234:235], v[200:201], v[104:105], v[234:235]
	v_pk_fma_f32 v[236:237], v[200:201], v[100:101], v[236:237]
	v_pk_fma_f32 v[238:239], v[200:201], v[96:97], v[238:239]
	v_pk_fma_f32 v[232:233], v[202:203], v[104:105], v[232:233]
	v_pk_fma_f32 v[234:235], v[202:203], v[100:101], v[234:235]
	v_pk_fma_f32 v[236:237], v[202:203], v[96:97], v[236:237]
	v_pk_fma_f32 v[238:239], v[202:203], v[250:251], v[238:239]
	v_exp_f32_e64 v240, -v232
	v_exp_f32_e64 v241, -v233
	v_exp_f32_e64 v242, -v234
	v_exp_f32_e64 v243, -v235
	v_exp_f32_e64 v244, -v236
	v_exp_f32_e64 v245, -v237
	v_exp_f32_e64 v246, -v238
	v_exp_f32_e64 v247, -v239
	v_pk_mul_f32 v[224:225], v[224:225], v[232:233]
	v_pk_mul_f32 v[226:227], v[226:227], v[234:235]
	v_pk_mul_f32 v[228:229], v[228:229], v[236:237]
	v_pk_mul_f32 v[230:231], v[230:231], v[238:239]
	v_pk_add_f32 v[240:241], v[240:241], 1.0 op_sel_hi:[1,0]
	v_pk_add_f32 v[242:243], v[242:243], 1.0 op_sel_hi:[1,0]
	v_pk_add_f32 v[244:245], v[244:245], 1.0 op_sel_hi:[1,0]
	v_pk_add_f32 v[246:247], v[246:247], 1.0 op_sel_hi:[1,0]
	v_rcp_f32_e32 v240, v240
	v_rcp_f32_e32 v241, v241
	v_rcp_f32_e32 v242, v242
	v_rcp_f32_e32 v243, v243
	v_rcp_f32_e32 v244, v244
	v_rcp_f32_e32 v245, v245
	v_rcp_f32_e32 v246, v246
	v_rcp_f32_e32 v247, v247
	s_nop 0
	v_pk_mul_f32 v[224:225], v[224:225], v[240:241]
	v_pk_mul_f32 v[226:227], v[226:227], v[242:243]
	v_pk_mul_f32 v[228:229], v[228:229], v[244:245]
	v_pk_mul_f32 v[230:231], v[230:231], v[246:247]
	v_cvt_pk_bf16_f32 v128, v224, v225
	v_cvt_pk_bf16_f32 v132, v226, v227
	v_cvt_pk_bf16_f32 v136, v228, v229
	v_cvt_pk_bf16_f32 v140, v230, v231
	global_load_dwordx4 v[190:193], v172, s[64:65] offset:128
	global_load_dwordx4 v[194:197], v172, s[64:65] offset:144
	global_load_dwordx4 v[198:201], v172, s[64:65] offset:160
	global_load_dwordx4 v[202:205], v172, s[64:65] offset:176
	s_waitcnt vmcnt(4)
;     __device__ __forceinline__ void operator()(const f32x4 (&acc)[2][2][4][2], const Unit& u, int wr, int wc, int fr, int fq) const {
;     ...
;                     const int cidx = (4 * n + 2 * jp) * 2;
;                     const f32x4 c0a = ct[cidx], c0b = ct[cidx + 1], c1a = ct[cidx + 2], c1b = ct[cidx + 3];
;                     const f32x2 wv0 = {c0a[0], c1a[0]}, wv1 = {c0a[1], c1a[1]}, wv2 = {c0a[2], c1a[2]}, bv = {c0a[3], c1a[3]};
;                     const f32x2 wg0 = {c0b[0], c1b[0]}, wg1 = {c0b[1], c1b[1]}, wg2 = {c0b[2], c1b[2]}, bg = {c0b[3], c1b[3]};
;                     f32x2 uv[4], ug[4], cv[4];
; #pragma unroll
;                     for (int m = 0; m < 4; ++m) { uv[m] = (f32x2){acc[ai][0][m][n][2 * jp], acc[ai][0][m][n][2 * jp + 1]}; ug[m] = (f32x2){acc[ai][1][m][n][2 * jp], acc[ai][1][m][n][2 * jp + 1]}; }
;                     asm volatile("" : "+v"(uv[0]), "+v"(uv[1]), "+v"(uv[2]), "+v"(uv[3]), "+v"(ug[0]), "+v"(ug[1]), "+v"(ug[2]), "+v"(ug[3]));
;                     {
;                         f32x2 rv[4], lv[4];
; #pragma unroll
;                         for (int m = 0; m < 4; ++m) { uv[m] = uv[m] * rs[m]; rv[m] = (f32x2){dpp_ror1(uv[m][0]), dpp_ror1(uv[m][1])}; lv[m] = (f32x2){dpp_ror15(uv[m][0]), dpp_ror15(uv[m][1])}; }
; #pragma unroll
;                         for (int m = 0; m < 4; ++m) { const f32x2 pv_ = (m > 0 && f0) ? rv[m > 0 ? m - 1 : 0] : rv[m], nv_ = (m < 3 && f15) ? lv[m < 3 ? m + 1 : 3] : lv[m];
;                             cv[m] = bv + wv0 * pv_ + wv1 * uv[m] + wv2 * nv_; }
;                     }
;                     asm volatile("" : "+v"(cv[0]), "+v"(cv[1]), "+v"(cv[2]), "+v"(cv[3]));
;                     {
;                         f32x2 rg[4], lg[4];
; #pragma unroll
;                         for (int m = 0; m < 4; ++m) { ug[m] = ug[m] * rs[m]; rg[m] = (f32x2){dpp_ror1(ug[m][0]), dpp_ror1(ug[m][1])}; lg[m] = (f32x2){dpp_ror15(ug[m][0]), dpp_ror15(ug[m][1])}; }
; #pragma unroll
;                         for (int m = 0; m < 4; ++m) { const f32x2 pg_ = (m > 0 && f0) ? rg[m > 0 ? m - 1 : 0] : rg[m], ng_ = (m < 3 && f15) ? lg[m < 3 ? m + 1 : 3] : lg[m];
;                             const f32x2 cgt = bg + wg0 * pg_ + wg1 * ug[m] + wg2 * ng_;
;                             const f32x2 e = cgt * (-LOG2E);
;                             const f32x2 d = (f32x2){__builtin_amdgcn_exp2f(e[0]), __builtin_amdgcn_exp2f(e[1])} + 1.f;
	v_pk_mul_f32 v[126:127], v[126:127], v[178:179] op_sel_hi:[1,0]
	v_pk_mul_f32 v[122:123], v[122:123], v[180:181] op_sel_hi:[1,0]
	v_pk_mul_f32 v[118:119], v[118:119], v[182:183] op_sel_hi:[1,0]
	v_pk_mul_f32 v[114:115], v[114:115], v[144:145] op_sel_hi:[1,0]
	v_pk_mul_f32 v[110:111], v[110:111], v[178:179] op_sel_hi:[1,0]
	v_pk_mul_f32 v[106:107], v[106:107], v[180:181] op_sel_hi:[1,0]
	v_pk_mul_f32 v[102:103], v[102:103], v[182:183] op_sel_hi:[1,0]
	v_pk_mul_f32 v[98:99], v[98:99], v[144:145] op_sel_hi:[1,0]
	s_nop 1
	v_mov_b32_dpp v248, v114 row_shr:1 row_mask:0xf bank_mask:0xf bound_ctrl:1
	v_mov_b32_dpp v249, v115 row_shr:1 row_mask:0xf bank_mask:0xf bound_ctrl:1
	v_mov_b32_dpp v250, v126 row_shl:1 row_mask:0xf bank_mask:0xf bound_ctrl:1
	v_mov_b32_dpp v251, v127 row_shl:1 row_mask:0xf bank_mask:0xf bound_ctrl:1
	v_pk_fma_f32 v[224:225], v[206:207], v[248:249], v[212:213]
	v_pk_fma_f32 v[226:227], v[206:207], v[126:127], v[212:213]
	v_pk_fma_f32 v[228:229], v[206:207], v[122:123], v[212:213]
	v_pk_fma_f32 v[230:231], v[206:207], v[118:119], v[212:213]
	v_pk_fma_f32 v[224:225], v[208:209], v[126:127], v[224:225]
	v_pk_fma_f32 v[226:227], v[208:209], v[122:123], v[226:227]
	v_pk_fma_f32 v[228:229], v[208:209], v[118:119], v[228:229]
	v_pk_fma_f32 v[230:231], v[208:209], v[114:115], v[230:231]
	v_pk_fma_f32 v[224:225], v[210:211], v[122:123], v[224:225]
	v_pk_fma_f32 v[226:227], v[210:211], v[118:119], v[226:227]
	v_pk_fma_f32 v[228:229], v[210:211], v[114:115], v[228:229]
	v_pk_fma_f32 v[230:231], v[210:211], v[250:251], v[230:231]
	s_nop 1
	v_mov_b32_dpp v248, v98 row_shr:1 row_mask:0xf bank_mask:0xf bound_ctrl:1
	v_mov_b32_dpp v249, v99 row_shr:1 row_mask:0xf bank_mask:0xf bound_ctrl:1
	v_mov_b32_dpp v250, v110 row_shl:1 row_mask:0xf bank_mask:0xf bound_ctrl:1
	v_mov_b32_dpp v251, v111 row_shl:1 row_mask:0xf bank_mask:0xf bound_ctrl:1
	v_pk_fma_f32 v[232:233], v[214:215], v[248:249], v[220:221]
	v_pk_fma_f32 v[234:235], v[214:215], v[110:111], v[220:221]
	v_pk_fma_f32 v[236:237], v[214:215], v[106:107], v[220:221]
	v_pk_fma_f32 v[238:239], v[214:215], v[102:103], v[220:221]
	v_pk_fma_f32 v[232:233], v[216:217], v[110:111], v[232:233]
	v_pk_fma_f32 v[234:235], v[216:217], v[106:107], v[234:235]
	v_pk_fma_f32 v[236:237], v[216:217], v[102:103], v[236:237]
	v_pk_fma_f32 v[238:239], v[216:217], v[98:99], v[238:239]
	v_pk_fma_f32 v[232:233], v[218:219], v[106:107], v[232:233]
	v_pk_fma_f32 v[234:235], v[218:219], v[102:103], v[234:235]
	v_pk_fma_f32 v[236:237], v[218:219], v[98:99], v[236:237]
	v_pk_fma_f32 v[238:239], v[218:219], v[250:251], v[238:239]
	v_exp_f32_e64 v240, -v232
	v_exp_f32_e64 v241, -v233
	v_exp_f32_e64 v242, -v234
	v_exp_f32_e64 v243, -v235
	v_exp_f32_e64 v244, -v236
	v_exp_f32_e64 v245, -v237
	v_exp_f32_e64 v246, -v238
	v_exp_f32_e64 v247, -v239
	v_pk_mul_f32 v[224:225], v[224:225], v[232:233]
	v_pk_mul_f32 v[226:227], v[226:227], v[234:235]
	v_pk_mul_f32 v[228:229], v[228:229], v[236:237]
	v_pk_mul_f32 v[230:231], v[230:231], v[238:239]
	v_pk_add_f32 v[240:241], v[240:241], 1.0 op_sel_hi:[1,0]
	v_pk_add_f32 v[242:243], v[242:243], 1.0 op_sel_hi:[1,0]
	v_pk_add_f32 v[244:245], v[244:245], 1.0 op_sel_hi:[1,0]
	v_pk_add_f32 v[246:247], v[246:247], 1.0 op_sel_hi:[1,0]
	v_rcp_f32_e32 v240, v240
	v_rcp_f32_e32 v241, v241
	v_rcp_f32_e32 v242, v242
	v_rcp_f32_e32 v243, v243
	v_rcp_f32_e32 v244, v244
	v_rcp_f32_e32 v245, v245
	v_rcp_f32_e32 v246, v246
	v_rcp_f32_e32 v247, v247
	s_nop 0
	v_pk_mul_f32 v[224:225], v[224:225], v[240:241]
	v_pk_mul_f32 v[226:227], v[226:227], v[242:243]
	v_pk_mul_f32 v[228:229], v[228:229], v[244:245]
	v_pk_mul_f32 v[230:231], v[230:231], v[246:247]
	v_cvt_pk_bf16_f32 v129, v224, v225
	v_cvt_pk_bf16_f32 v133, v226, v227
	v_cvt_pk_bf16_f32 v137, v228, v229
	v_cvt_pk_bf16_f32 v141, v230, v231
	global_load_dwordx4 v[206:209], v172, s[64:65] offset:192
	global_load_dwordx4 v[210:213], v172, s[64:65] offset:208
	global_load_dwordx4 v[214:217], v172, s[64:65] offset:224
	global_load_dwordx4 v[218:221], v172, s[64:65] offset:240
	s_waitcnt vmcnt(4)
	v_pk_mul_f32 v[92:93], v[92:93], v[178:179] op_sel_hi:[1,0]
	v_pk_mul_f32 v[88:89], v[88:89], v[180:181] op_sel_hi:[1,0]
	v_pk_mul_f32 v[84:85], v[84:85], v[182:183] op_sel_hi:[1,0]
	v_pk_mul_f32 v[80:81], v[80:81], v[144:145] op_sel_hi:[1,0]
	v_pk_mul_f32 v[76:77], v[76:77], v[178:179] op_sel_hi:[1,0]
	v_pk_mul_f32 v[72:73], v[72:73], v[180:181] op_sel_hi:[1,0]
	v_pk_mul_f32 v[68:69], v[68:69], v[182:183] op_sel_hi:[1,0]
	v_pk_mul_f32 v[64:65], v[64:65], v[144:145] op_sel_hi:[1,0]
	s_nop 1
	v_mov_b32_dpp v248, v80 row_shr:1 row_mask:0xf bank_mask:0xf bound_ctrl:1
	v_mov_b32_dpp v249, v81 row_shr:1 row_mask:0xf bank_mask:0xf bound_ctrl:1
	v_mov_b32_dpp v250, v92 row_shl:1 row_mask:0xf bank_mask:0xf bound_ctrl:1
	v_mov_b32_dpp v251, v93 row_shl:1 row_mask:0xf bank_mask:0xf bound_ctrl:1
	v_pk_fma_f32 v[224:225], v[190:191], v[248:249], v[196:197]
	v_pk_fma_f32 v[226:227], v[190:191], v[92:93], v[196:197]
	v_pk_fma_f32 v[228:229], v[190:191], v[88:89], v[196:197]
	v_pk_fma_f32 v[230:231], v[190:191], v[84:85], v[196:197]
	v_pk_fma_f32 v[224:225], v[192:193], v[92:93], v[224:225]
	v_pk_fma_f32 v[226:227], v[192:193], v[88:89], v[226:227]
	v_pk_fma_f32 v[228:229], v[192:193], v[84:85], v[228:229]
	v_pk_fma_f32 v[230:231], v[192:193], v[80:81], v[230:231]
	v_pk_fma_f32 v[224:225], v[194:195], v[88:89], v[224:225]
	v_pk_fma_f32 v[226:227], v[194:195], v[84:85], v[226:227]
	v_pk_fma_f32 v[228:229], v[194:195], v[80:81], v[228:229]
	v_pk_fma_f32 v[230:231], v[194:195], v[250:251], v[230:231]
	s_nop 1
	v_mov_b32_dpp v248, v64 row_shr:1 row_mask:0xf bank_mask:0xf bound_ctrl:1
; __device__ __forceinline__ unsigned cvtpk(float lo, float hi) { f32x2 v = {lo, hi}; bf16x2_t b = __builtin_convertvector(v, bf16x2_t); return __builtin_bit_cast(unsigned, b); }
; __device__ __forceinline__ float dpp_ror1(float x) { return __builtin_bit_cast(float, __builtin_amdgcn_mov_dpp(__builtin_bit_cast(int, x), 0x121, 0xF, 0xF, true)); }
; __device__ __forceinline__ float dpp_ror15(float x) { return __builtin_bit_cast(float, __builtin_amdgcn_mov_dpp(__builtin_bit_cast(int, x), 0x12F, 0xF, 0xF, true)); }
;     __device__ __forceinline__ void operator()(const f32x4 (&acc)[2][2][4][2], const Unit& u, int wr, int wc, int fr, int fq) const {
;     ...
;             for (int m = 0; m < 4; ++m) { const int t = tbase + 16 * m + fr; const bool vin = (t >= 0) && (t < slen); const int grow = seqbase + (vin ? t : 0);
;                 const f32x4 p = *(const f32x4*)(PS + (size_t)grow * 16 + 4 * fq); float s = (p[0] + p[1]) + (p[2] + p[3]); s = bfly_add<16>(s); s = bfly_add<32>(s); rs[m] = vin ? rsqrtf(s * (1.f / DM) + EPS) : 0.f; }
;     ...
;                         for (int m = 0; m < 4; ++m) { ug[m] = ug[m] * rs[m]; rg[m] = (f32x2){dpp_ror1(ug[m][0]), dpp_ror1(ug[m][1])}; lg[m] = (f32x2){dpp_ror15(ug[m][0]), dpp_ror15(ug[m][1])}; }
; #pragma unroll
;                         for (int m = 0; m < 4; ++m) { const f32x2 pg_ = (m > 0 && f0) ? rg[m > 0 ? m - 1 : 0] : rg[m], ng_ = (m < 3 && f15) ? lg[m < 3 ? m + 1 : 3] : lg[m];
;                             const f32x2 cgt = bg + wg0 * pg_ + wg1 * ug[m] + wg2 * ng_;
;                             const f32x2 e = cgt * (-LOG2E);
;                             const f32x2 d = (f32x2){__builtin_amdgcn_exp2f(e[0]), __builtin_amdgcn_exp2f(e[1])} + 1.f;
;                             const f32x2 sg = {__builtin_amdgcn_rcpf(d[0]), __builtin_amdgcn_rcpf(d[1])};
;                             const f32x2 ov = cv[m] * cgt * sg;
;                             outw[m][n][jp] = cvtpk(ov[0], ov[1]); }
;                     }
;                     asm volatile("" : "+v"(outw[0][n][jp]), "+v"(outw[1][n][jp]), "+v"(outw[2][n][jp]), "+v"(outw[3][n][jp]) :: "memory"); __builtin_amdgcn_sched_barrier(0);
	v_mov_b32_dpp v249, v65 row_shr:1 row_mask:0xf bank_mask:0xf bound_ctrl:1
	v_mov_b32_dpp v250, v76 row_shl:1 row_mask:0xf bank_mask:0xf bound_ctrl:1
	v_mov_b32_dpp v251, v77 row_shl:1 row_mask:0xf bank_mask:0xf bound_ctrl:1
	v_pk_fma_f32 v[232:233], v[198:199], v[248:249], v[204:205]
	v_pk_fma_f32 v[234:235], v[198:199], v[76:77], v[204:205]
	v_pk_fma_f32 v[236:237], v[198:199], v[72:73], v[204:205]
	v_pk_fma_f32 v[238:239], v[198:199], v[68:69], v[204:205]
	v_pk_fma_f32 v[232:233], v[200:201], v[76:77], v[232:233]
	v_pk_fma_f32 v[234:235], v[200:201], v[72:73], v[234:235]
	v_pk_fma_f32 v[236:237], v[200:201], v[68:69], v[236:237]
	v_pk_fma_f32 v[238:239], v[200:201], v[64:65], v[238:239]
	v_pk_fma_f32 v[232:233], v[202:203], v[72:73], v[232:233]
	v_pk_fma_f32 v[234:235], v[202:203], v[68:69], v[234:235]
	v_pk_fma_f32 v[236:237], v[202:203], v[64:65], v[236:237]
	v_pk_fma_f32 v[238:239], v[202:203], v[250:251], v[238:239]
	v_exp_f32_e64 v240, -v232
	v_exp_f32_e64 v241, -v233
	v_exp_f32_e64 v242, -v234
	v_exp_f32_e64 v243, -v235
	v_exp_f32_e64 v244, -v236
	v_exp_f32_e64 v245, -v237
	v_exp_f32_e64 v246, -v238
	v_exp_f32_e64 v247, -v239
	v_pk_mul_f32 v[224:225], v[224:225], v[232:233]
	v_pk_mul_f32 v[226:227], v[226:227], v[234:235]
	v_pk_mul_f32 v[228:229], v[228:229], v[236:237]
	v_pk_mul_f32 v[230:231], v[230:231], v[238:239]
	v_pk_add_f32 v[240:241], v[240:241], 1.0 op_sel_hi:[1,0]
	v_pk_add_f32 v[242:243], v[242:243], 1.0 op_sel_hi:[1,0]
	v_pk_add_f32 v[244:245], v[244:245], 1.0 op_sel_hi:[1,0]
	v_pk_add_f32 v[246:247], v[246:247], 1.0 op_sel_hi:[1,0]
	v_rcp_f32_e32 v240, v240
	v_rcp_f32_e32 v241, v241
	v_rcp_f32_e32 v242, v242
	v_rcp_f32_e32 v243, v243
	v_rcp_f32_e32 v244, v244
	v_rcp_f32_e32 v245, v245
	v_rcp_f32_e32 v246, v246
	v_rcp_f32_e32 v247, v247
	s_nop 0
	v_pk_mul_f32 v[224:225], v[224:225], v[240:241]
	v_pk_mul_f32 v[226:227], v[226:227], v[242:243]
	v_pk_mul_f32 v[228:229], v[228:229], v[244:245]
	v_pk_mul_f32 v[230:231], v[230:231], v[246:247]
	v_cvt_pk_bf16_f32 v130, v224, v225
	v_cvt_pk_bf16_f32 v134, v226, v227
	v_cvt_pk_bf16_f32 v138, v228, v229
	v_cvt_pk_bf16_f32 v142, v230, v231
	s_waitcnt vmcnt(0)
	v_add_u32_e32 v253, 0x7c, v174
	v_lshrrev_b32_e32 v176, 4, v165
	v_add_u32_e32 v176, v176, v253
	v_cmp_gt_u32_e32 vcc, s91, v176
	s_nop 1
	v_cndmask_b32_e32 v176, 0, v176, vcc
	v_add_u32_e32 v176, s88, v176
	v_lshlrev_b32_e32 v248, 6, v176
	global_load_dwordx4 v[190:193], v248, s[70:71]
	global_load_dwordx4 v[194:197], v248, s[70:71] offset:16
	global_load_dwordx4 v[198:201], v248, s[70:71] offset:32
	global_load_dwordx4 v[202:205], v248, s[70:71] offset:48
	v_pk_mul_f32 v[94:95], v[94:95], v[178:179] op_sel_hi:[1,0]
	v_pk_mul_f32 v[90:91], v[90:91], v[180:181] op_sel_hi:[1,0]
	v_pk_mul_f32 v[86:87], v[86:87], v[182:183] op_sel_hi:[1,0]
	v_pk_mul_f32 v[82:83], v[82:83], v[144:145] op_sel_hi:[1,0]
	v_pk_mul_f32 v[78:79], v[78:79], v[178:179] op_sel_hi:[1,0]
	v_pk_mul_f32 v[74:75], v[74:75], v[180:181] op_sel_hi:[1,0]
	v_pk_mul_f32 v[70:71], v[70:71], v[182:183] op_sel_hi:[1,0]
	v_pk_mul_f32 v[66:67], v[66:67], v[144:145] op_sel_hi:[1,0]
	s_nop 1
	v_mov_b32_dpp v248, v82 row_shr:1 row_mask:0xf bank_mask:0xf bound_ctrl:1
	v_mov_b32_dpp v249, v83 row_shr:1 row_mask:0xf bank_mask:0xf bound_ctrl:1
	v_mov_b32_dpp v250, v94 row_shl:1 row_mask:0xf bank_mask:0xf bound_ctrl:1
	v_mov_b32_dpp v251, v95 row_shl:1 row_mask:0xf bank_mask:0xf bound_ctrl:1
	v_pk_fma_f32 v[224:225], v[206:207], v[248:249], v[212:213]
	v_pk_fma_f32 v[226:227], v[206:207], v[94:95], v[212:213]
	v_pk_fma_f32 v[228:229], v[206:207], v[90:91], v[212:213]
	v_pk_fma_f32 v[230:231], v[206:207], v[86:87], v[212:213]
	v_pk_fma_f32 v[224:225], v[208:209], v[94:95], v[224:225]
	v_pk_fma_f32 v[226:227], v[208:209], v[90:91], v[226:227]
	v_pk_fma_f32 v[228:229], v[208:209], v[86:87], v[228:229]
	v_pk_fma_f32 v[230:231], v[208:209], v[82:83], v[230:231]
	v_pk_fma_f32 v[224:225], v[210:211], v[90:91], v[224:225]
	v_pk_fma_f32 v[226:227], v[210:211], v[86:87], v[226:227]
	v_pk_fma_f32 v[228:229], v[210:211], v[82:83], v[228:229]
	v_pk_fma_f32 v[230:231], v[210:211], v[250:251], v[230:231]
	s_nop 1
	v_mov_b32_dpp v248, v66 row_shr:1 row_mask:0xf bank_mask:0xf bound_ctrl:1
	v_mov_b32_dpp v249, v67 row_shr:1 row_mask:0xf bank_mask:0xf bound_ctrl:1
	v_mov_b32_dpp v250, v78 row_shl:1 row_mask:0xf bank_mask:0xf bound_ctrl:1
	v_mov_b32_dpp v251, v79 row_shl:1 row_mask:0xf bank_mask:0xf bound_ctrl:1
	v_pk_fma_f32 v[232:233], v[214:215], v[248:249], v[220:221]
	v_pk_fma_f32 v[234:235], v[214:215], v[78:79], v[220:221]
	v_pk_fma_f32 v[236:237], v[214:215], v[74:75], v[220:221]
	v_pk_fma_f32 v[238:239], v[214:215], v[70:71], v[220:221]
	v_pk_fma_f32 v[232:233], v[216:217], v[78:79], v[232:233]
	v_pk_fma_f32 v[234:235], v[216:217], v[74:75], v[234:235]
	v_pk_fma_f32 v[236:237], v[216:217], v[70:71], v[236:237]
	v_pk_fma_f32 v[238:239], v[216:217], v[66:67], v[238:239]
	v_pk_fma_f32 v[232:233], v[218:219], v[74:75], v[232:233]
	v_pk_fma_f32 v[234:235], v[218:219], v[70:71], v[234:235]
	v_pk_fma_f32 v[236:237], v[218:219], v[66:67], v[236:237]
	v_pk_fma_f32 v[238:239], v[218:219], v[250:251], v[238:239]
	v_exp_f32_e64 v240, -v232
	v_exp_f32_e64 v241, -v233
	v_exp_f32_e64 v242, -v234
	v_exp_f32_e64 v243, -v235
	v_exp_f32_e64 v244, -v236
	v_exp_f32_e64 v245, -v237
	v_exp_f32_e64 v246, -v238
	v_exp_f32_e64 v247, -v239
	v_pk_mul_f32 v[224:225], v[224:225], v[232:233]
	v_pk_mul_f32 v[226:227], v[226:227], v[234:235]
	v_pk_mul_f32 v[228:229], v[228:229], v[236:237]
	v_pk_mul_f32 v[230:231], v[230:231], v[238:239]
	v_pk_add_f32 v[240:241], v[240:241], 1.0 op_sel_hi:[1,0]
; __device__ __forceinline__ unsigned cvtpk(float lo, float hi) { f32x2 v = {lo, hi}; bf16x2_t b = __builtin_convertvector(v, bf16x2_t); return __builtin_bit_cast(unsigned, b); }
;     __device__ __forceinline__ void operator()(const f32x4 (&acc)[2][2][4][2], const Unit& u, int wr, int wc, int fr, int fq) const {
;     ...
;             for (int m = 0; m < 4; ++m) { const int t = tbase + 16 * m + fr; const bool vin = (t >= 0) && (t < slen); const int grow = seqbase + (vin ? t : 0);
;                 const f32x4 p = *(const f32x4*)(PS + (size_t)grow * 16 + 4 * fq); float s = (p[0] + p[1]) + (p[2] + p[3]); s = bfly_add<16>(s); s = bfly_add<32>(s); rs[m] = vin ? rsqrtf(s * (1.f / DM) + EPS) : 0.f; }
;     ...
;                             outw[m][n][jp] = cvtpk(ov[0], ov[1]); }
;                     }
;                     asm volatile("" : "+v"(outw[0][n][jp]), "+v"(outw[1][n][jp]), "+v"(outw[2][n][jp]), "+v"(outw[3][n][jp]) :: "memory"); __builtin_amdgcn_sched_barrier(0);
;                 }
; #pragma unroll
;             for (int m = 0; m < 4; ++m) { const int i = 16 * m + fr, t = tbase + i;
;                 if (i >= 1 && i <= 62 && t < slen) { u32x4 w; w.x = outw[m][0][0]; w.y = outw[m][0][1]; w.z = outw[m][1][0]; w.w = outw[m][1][1];
;                     *(u32x4*)(Gout + (size_t)(seqbase + t) * DFF + 128 * u.pn + 32 * wc + 8 * fq) = w; } }
	v_pk_add_f32 v[242:243], v[242:243], 1.0 op_sel_hi:[1,0]
	v_pk_add_f32 v[244:245], v[244:245], 1.0 op_sel_hi:[1,0]
	v_pk_add_f32 v[246:247], v[246:247], 1.0 op_sel_hi:[1,0]
	v_rcp_f32_e32 v240, v240
	v_rcp_f32_e32 v241, v241
	v_rcp_f32_e32 v242, v242
	v_rcp_f32_e32 v243, v243
	v_rcp_f32_e32 v244, v244
	v_rcp_f32_e32 v245, v245
	v_rcp_f32_e32 v246, v246
	v_rcp_f32_e32 v247, v247
	s_nop 0
	v_pk_mul_f32 v[224:225], v[224:225], v[240:241]
	v_pk_mul_f32 v[226:227], v[226:227], v[242:243]
	v_pk_mul_f32 v[228:229], v[228:229], v[244:245]
	v_pk_mul_f32 v[230:231], v[230:231], v[246:247]
	v_cvt_pk_bf16_f32 v131, v224, v225
	v_cvt_pk_bf16_f32 v135, v226, v227
	v_cvt_pk_bf16_f32 v139, v228, v229
	v_cvt_pk_bf16_f32 v143, v230, v231
	s_sub_i32 s51, s91, s89
	s_sub_i32 s66, s51, 4
	s_max_i32 s66, s66, 0
	v_add_u32_e32 v176, -4, v164
	v_cmp_gt_u32_e32 vcc, s66, v176
	v_add_u32_e32 v176, 0, v174
	v_add_u32_e32 v176, s88, v176
	v_mad_u32_u24 v248, v176, s54, v165
	s_mov_b64 exec, vcc
	global_store_dwordx4 v248, v[128:131], s[86:87]
	s_mov_b64 exec, -1
	s_sub_i32 s66, s51, 1
	s_max_i32 s66, s66, 0
	v_cmp_gt_u32_e32 vcc, s66, v164
	v_add_u32_e32 v176, 1, v174
	v_add_u32_e32 v176, s88, v176
	v_mad_u32_u24 v249, v176, s54, v165
	s_mov_b64 exec, vcc
	global_store_dwordx4 v249, v[132:135], s[86:87]
	s_mov_b64 exec, -1
	s_sub_i32 s66, s51, 2
	s_max_i32 s66, s66, 0
	v_cmp_gt_u32_e32 vcc, s66, v164
	v_add_u32_e32 v176, 2, v174
	v_add_u32_e32 v176, s88, v176
	v_mad_u32_u24 v250, v176, s54, v165
	s_mov_b64 exec, vcc
	global_store_dwordx4 v250, v[136:139], s[86:87]
	s_mov_b64 exec, -1
	s_sub_i32 s66, s51, 3
	s_min_i32 s66, s66, 60
	s_max_i32 s66, s66, 0
	v_cmp_gt_u32_e32 vcc, s66, v164
	v_add_u32_e32 v176, 3, v174
	v_add_u32_e32 v176, s88, v176
	v_mad_u32_u24 v251, v176, s54, v165
	s_mov_b64 exec, vcc
	global_store_dwordx4 v251, v[140:143], s[86:87]
	s_mov_b64 exec, -1
	s_addk_i32 s89, 0x7c
	v_mov_b32_e32 v174, v253
	global_load_dwordx4 v[206:209], v172, s[64:65]
	global_load_dwordx4 v[210:213], v172, s[64:65] offset:16
	global_load_dwordx4 v[214:217], v172, s[64:65] offset:32
	global_load_dwordx4 v[218:221], v172, s[64:65] offset:48
	v_lshrrev_b32_e32 v176, 4, v165
	v_add_u32_e32 v176, v176, v174
	v_cmp_gt_u32_e32 vcc, s91, v176
	s_waitcnt vmcnt(8)
	v_pk_add_f32 v[190:191], v[190:191], v[194:195]
	v_pk_add_f32 v[192:193], v[192:193], v[196:197]
	v_pk_add_f32 v[198:199], v[198:199], v[202:203]
	v_pk_add_f32 v[200:201], v[200:201], v[204:205]
	v_pk_add_f32 v[190:191], v[190:191], v[198:199]
	v_pk_add_f32 v[192:193], v[192:193], v[200:201]
	v_pk_add_f32 v[190:191], v[190:191], v[192:193]
	v_add_f32_e32 v190, v190, v191
	v_fma_f32 v190, v190, s82, v252
	v_rsq_f32_e32 v190, v190
	s_nop 0
	v_cndmask_b32_e32 v178, 0, v190, vcc
	v_mov_b32_e32 v180, v178
	s_nop 1
	v_permlane16_swap_b32_e32 v178, v180
	v_mov_b32_e32 v182, v178
	v_mov_b32_e32 v144, v180
	s_nop 1
	v_permlane32_swap_b32_e32 v178, v182
	v_permlane32_swap_b32_e32 v180, v144
	global_load_dwordx4 v[190:193], v172, s[64:65] offset:64
	global_load_dwordx4 v[194:197], v172, s[64:65] offset:80
	global_load_dwordx4 v[198:201], v172, s[64:65] offset:96
	global_load_dwordx4 v[202:205], v172, s[64:65] offset:112
	s_waitcnt vmcnt(4)
	v_pk_mul_f32 v[60:61], v[60:61], v[178:179] op_sel_hi:[1,0]
	v_pk_mul_f32 v[56:57], v[56:57], v[180:181] op_sel_hi:[1,0]
	v_pk_mul_f32 v[52:53], v[52:53], v[182:183] op_sel_hi:[1,0]
	v_pk_mul_f32 v[48:49], v[48:49], v[144:145] op_sel_hi:[1,0]
	v_pk_mul_f32 v[44:45], v[44:45], v[178:179] op_sel_hi:[1,0]
	v_pk_mul_f32 v[40:41], v[40:41], v[180:181] op_sel_hi:[1,0]
	v_pk_mul_f32 v[36:37], v[36:37], v[182:183] op_sel_hi:[1,0]
	v_pk_mul_f32 v[32:33], v[32:33], v[144:145] op_sel_hi:[1,0]
	s_nop 1
	v_mov_b32_dpp v248, v48 row_shr:1 row_mask:0xf bank_mask:0xf bound_ctrl:1
	v_mov_b32_dpp v249, v49 row_shr:1 row_mask:0xf bank_mask:0xf bound_ctrl:1
	v_mov_b32_dpp v250, v60 row_shl:1 row_mask:0xf bank_mask:0xf bound_ctrl:1
	v_mov_b32_dpp v251, v61 row_shl:1 row_mask:0xf bank_mask:0xf bound_ctrl:1
	v_pk_fma_f32 v[224:225], v[206:207], v[248:249], v[212:213]
	v_pk_fma_f32 v[226:227], v[206:207], v[60:61], v[212:213]
	v_pk_fma_f32 v[228:229], v[206:207], v[56:57], v[212:213]
	v_pk_fma_f32 v[230:231], v[206:207], v[52:53], v[212:213]
	v_pk_fma_f32 v[224:225], v[208:209], v[60:61], v[224:225]
	v_pk_fma_f32 v[226:227], v[208:209], v[56:57], v[226:227]
	v_pk_fma_f32 v[228:229], v[208:209], v[52:53], v[228:229]
	v_pk_fma_f32 v[230:231], v[208:209], v[48:49], v[230:231]
	v_pk_fma_f32 v[224:225], v[210:211], v[56:57], v[224:225]
	v_pk_fma_f32 v[226:227], v[210:211], v[52:53], v[226:227]
	v_pk_fma_f32 v[228:229], v[210:211], v[48:49], v[228:229]
	v_pk_fma_f32 v[230:231], v[210:211], v[250:251], v[230:231]
	s_nop 1
	v_mov_b32_dpp v248, v32 row_shr:1 row_mask:0xf bank_mask:0xf bound_ctrl:1
	v_mov_b32_dpp v249, v33 row_shr:1 row_mask:0xf bank_mask:0xf bound_ctrl:1
	v_mov_b32_dpp v250, v44 row_shl:1 row_mask:0xf bank_mask:0xf bound_ctrl:1
	v_mov_b32_dpp v251, v45 row_shl:1 row_mask:0xf bank_mask:0xf bound_ctrl:1
	v_pk_fma_f32 v[232:233], v[214:215], v[248:249], v[220:221]
	v_pk_fma_f32 v[234:235], v[214:215], v[44:45], v[220:221]
	v_pk_fma_f32 v[236:237], v[214:215], v[40:41], v[220:221]
	v_pk_fma_f32 v[238:239], v[214:215], v[36:37], v[220:221]
	v_pk_fma_f32 v[232:233], v[216:217], v[44:45], v[232:233]
	v_pk_fma_f32 v[234:235], v[216:217], v[40:41], v[234:235]
	v_pk_fma_f32 v[236:237], v[216:217], v[36:37], v[236:237]
	v_pk_fma_f32 v[238:239], v[216:217], v[32:33], v[238:239]
	v_pk_fma_f32 v[232:233], v[218:219], v[40:41], v[232:233]
	v_pk_fma_f32 v[234:235], v[218:219], v[36:37], v[234:235]
;     __device__ __forceinline__ void operator()(const f32x4 (&acc)[2][2][4][2], const Unit& u, int wr, int wc, int fr, int fq) const {
;     ...
;                     const int cidx = (4 * n + 2 * jp) * 2;
;                     const f32x4 c0a = ct[cidx], c0b = ct[cidx + 1], c1a = ct[cidx + 2], c1b = ct[cidx + 3];
;                     const f32x2 wv0 = {c0a[0], c1a[0]}, wv1 = {c0a[1], c1a[1]}, wv2 = {c0a[2], c1a[2]}, bv = {c0a[3], c1a[3]};
;                     const f32x2 wg0 = {c0b[0], c1b[0]}, wg1 = {c0b[1], c1b[1]}, wg2 = {c0b[2], c1b[2]}, bg = {c0b[3], c1b[3]};
;                     f32x2 uv[4], ug[4], cv[4];
; #pragma unroll
;                     for (int m = 0; m < 4; ++m) { uv[m] = (f32x2){acc[ai][0][m][n][2 * jp], acc[ai][0][m][n][2 * jp + 1]}; ug[m] = (f32x2){acc[ai][1][m][n][2 * jp], acc[ai][1][m][n][2 * jp + 1]}; }
;                     asm volatile("" : "+v"(uv[0]), "+v"(uv[1]), "+v"(uv[2]), "+v"(uv[3]), "+v"(ug[0]), "+v"(ug[1]), "+v"(ug[2]), "+v"(ug[3]));
;                     {
;                         f32x2 rv[4], lv[4];
; #pragma unroll
;                         for (int m = 0; m < 4; ++m) { uv[m] = uv[m] * rs[m]; rv[m] = (f32x2){dpp_ror1(uv[m][0]), dpp_ror1(uv[m][1])}; lv[m] = (f32x2){dpp_ror15(uv[m][0]), dpp_ror15(uv[m][1])}; }
; #pragma unroll
;                         for (int m = 0; m < 4; ++m) { const f32x2 pv_ = (m > 0 && f0) ? rv[m > 0 ? m - 1 : 0] : rv[m], nv_ = (m < 3 && f15) ? lv[m < 3 ? m + 1 : 3] : lv[m];
;                             cv[m] = bv + wv0 * pv_ + wv1 * uv[m] + wv2 * nv_; }
;                     }
;                     asm volatile("" : "+v"(cv[0]), "+v"(cv[1]), "+v"(cv[2]), "+v"(cv[3]));
;                     {
;                         f32x2 rg[4], lg[4];
; #pragma unroll
;                         for (int m = 0; m < 4; ++m) { ug[m] = ug[m] * rs[m]; rg[m] = (f32x2){dpp_ror1(ug[m][0]), dpp_ror1(ug[m][1])}; lg[m] = (f32x2){dpp_ror15(ug[m][0]), dpp_ror15(ug[m][1])}; }
; #pragma unroll
;                         for (int m = 0; m < 4; ++m) { const f32x2 pg_ = (m > 0 && f0) ? rg[m > 0 ? m - 1 : 0] : rg[m], ng_ = (m < 3 && f15) ? lg[m < 3 ? m + 1 : 3] : lg[m];
;                             const f32x2 cgt = bg + wg0 * pg_ + wg1 * ug[m] + wg2 * ng_;
;                             const f32x2 e = cgt * (-LOG2E);
;                             const f32x2 d = (f32x2){__builtin_amdgcn_exp2f(e[0]), __builtin_amdgcn_exp2f(e[1])} + 1.f;
	v_pk_fma_f32 v[236:237], v[218:219], v[32:33], v[236:237]
	v_pk_fma_f32 v[238:239], v[218:219], v[250:251], v[238:239]
	v_exp_f32_e64 v240, -v232
	v_exp_f32_e64 v241, -v233
	v_exp_f32_e64 v242, -v234
	v_exp_f32_e64 v243, -v235
	v_exp_f32_e64 v244, -v236
	v_exp_f32_e64 v245, -v237
	v_exp_f32_e64 v246, -v238
	v_exp_f32_e64 v247, -v239
	v_pk_mul_f32 v[224:225], v[224:225], v[232:233]
	v_pk_mul_f32 v[226:227], v[226:227], v[234:235]
	v_pk_mul_f32 v[228:229], v[228:229], v[236:237]
	v_pk_mul_f32 v[230:231], v[230:231], v[238:239]
	v_pk_add_f32 v[240:241], v[240:241], 1.0 op_sel_hi:[1,0]
	v_pk_add_f32 v[242:243], v[242:243], 1.0 op_sel_hi:[1,0]
	v_pk_add_f32 v[244:245], v[244:245], 1.0 op_sel_hi:[1,0]
	v_pk_add_f32 v[246:247], v[246:247], 1.0 op_sel_hi:[1,0]
	v_rcp_f32_e32 v240, v240
	v_rcp_f32_e32 v241, v241
	v_rcp_f32_e32 v242, v242
	v_rcp_f32_e32 v243, v243
	v_rcp_f32_e32 v244, v244
	v_rcp_f32_e32 v245, v245
	v_rcp_f32_e32 v246, v246
	v_rcp_f32_e32 v247, v247
	s_nop 0
	v_pk_mul_f32 v[224:225], v[224:225], v[240:241]
	v_pk_mul_f32 v[226:227], v[226:227], v[242:243]
	v_pk_mul_f32 v[228:229], v[228:229], v[244:245]
	v_pk_mul_f32 v[230:231], v[230:231], v[246:247]
	v_cvt_pk_bf16_f32 v128, v224, v225
	v_cvt_pk_bf16_f32 v132, v226, v227
	v_cvt_pk_bf16_f32 v136, v228, v229
	v_cvt_pk_bf16_f32 v140, v230, v231
	global_load_dwordx4 v[206:209], v172, s[64:65] offset:128
	global_load_dwordx4 v[210:213], v172, s[64:65] offset:144
	global_load_dwordx4 v[214:217], v172, s[64:65] offset:160
	global_load_dwordx4 v[218:221], v172, s[64:65] offset:176
	s_waitcnt vmcnt(4)
	v_pk_mul_f32 v[62:63], v[62:63], v[178:179] op_sel_hi:[1,0]
	v_pk_mul_f32 v[58:59], v[58:59], v[180:181] op_sel_hi:[1,0]
	v_pk_mul_f32 v[54:55], v[54:55], v[182:183] op_sel_hi:[1,0]
	v_pk_mul_f32 v[50:51], v[50:51], v[144:145] op_sel_hi:[1,0]
	v_pk_mul_f32 v[46:47], v[46:47], v[178:179] op_sel_hi:[1,0]
	v_pk_mul_f32 v[42:43], v[42:43], v[180:181] op_sel_hi:[1,0]
	v_pk_mul_f32 v[38:39], v[38:39], v[182:183] op_sel_hi:[1,0]
	v_pk_mul_f32 v[34:35], v[34:35], v[144:145] op_sel_hi:[1,0]
	s_nop 1
	v_mov_b32_dpp v248, v50 row_shr:1 row_mask:0xf bank_mask:0xf bound_ctrl:1
	v_mov_b32_dpp v249, v51 row_shr:1 row_mask:0xf bank_mask:0xf bound_ctrl:1
	v_mov_b32_dpp v250, v62 row_shl:1 row_mask:0xf bank_mask:0xf bound_ctrl:1
	v_mov_b32_dpp v251, v63 row_shl:1 row_mask:0xf bank_mask:0xf bound_ctrl:1
	v_pk_fma_f32 v[224:225], v[190:191], v[248:249], v[196:197]
	v_pk_fma_f32 v[226:227], v[190:191], v[62:63], v[196:197]
	v_pk_fma_f32 v[228:229], v[190:191], v[58:59], v[196:197]
	v_pk_fma_f32 v[230:231], v[190:191], v[54:55], v[196:197]
	v_pk_fma_f32 v[224:225], v[192:193], v[62:63], v[224:225]
	v_pk_fma_f32 v[226:227], v[192:193], v[58:59], v[226:227]
	v_pk_fma_f32 v[228:229], v[192:193], v[54:55], v[228:229]
	v_pk_fma_f32 v[230:231], v[192:193], v[50:51], v[230:231]
	v_pk_fma_f32 v[224:225], v[194:195], v[58:59], v[224:225]
	v_pk_fma_f32 v[226:227], v[194:195], v[54:55], v[226:227]
	v_pk_fma_f32 v[228:229], v[194:195], v[50:51], v[228:229]
	v_pk_fma_f32 v[230:231], v[194:195], v[250:251], v[230:231]
	s_nop 1
	v_mov_b32_dpp v248, v34 row_shr:1 row_mask:0xf bank_mask:0xf bound_ctrl:1
	v_mov_b32_dpp v249, v35 row_shr:1 row_mask:0xf bank_mask:0xf bound_ctrl:1
	v_mov_b32_dpp v250, v46 row_shl:1 row_mask:0xf bank_mask:0xf bound_ctrl:1
	v_mov_b32_dpp v251, v47 row_shl:1 row_mask:0xf bank_mask:0xf bound_ctrl:1
	v_pk_fma_f32 v[232:233], v[198:199], v[248:249], v[204:205]
	v_pk_fma_f32 v[234:235], v[198:199], v[46:47], v[204:205]
	v_pk_fma_f32 v[236:237], v[198:199], v[42:43], v[204:205]
	v_pk_fma_f32 v[238:239], v[198:199], v[38:39], v[204:205]
	v_pk_fma_f32 v[232:233], v[200:201], v[46:47], v[232:233]
	v_pk_fma_f32 v[234:235], v[200:201], v[42:43], v[234:235]
	v_pk_fma_f32 v[236:237], v[200:201], v[38:39], v[236:237]
	v_pk_fma_f32 v[238:239], v[200:201], v[34:35], v[238:239]
	v_pk_fma_f32 v[232:233], v[202:203], v[42:43], v[232:233]
	v_pk_fma_f32 v[234:235], v[202:203], v[38:39], v[234:235]
	v_pk_fma_f32 v[236:237], v[202:203], v[34:35], v[236:237]
	v_pk_fma_f32 v[238:239], v[202:203], v[250:251], v[238:239]
	v_exp_f32_e64 v240, -v232
	v_exp_f32_e64 v241, -v233
	v_exp_f32_e64 v242, -v234
	v_exp_f32_e64 v243, -v235
	v_exp_f32_e64 v244, -v236
	v_exp_f32_e64 v245, -v237
	v_exp_f32_e64 v246, -v238
	v_exp_f32_e64 v247, -v239
	v_pk_mul_f32 v[224:225], v[224:225], v[232:233]
	v_pk_mul_f32 v[226:227], v[226:227], v[234:235]
	v_pk_mul_f32 v[228:229], v[228:229], v[236:237]
	v_pk_mul_f32 v[230:231], v[230:231], v[238:239]
	v_pk_add_f32 v[240:241], v[240:241], 1.0 op_sel_hi:[1,0]
	v_pk_add_f32 v[242:243], v[242:243], 1.0 op_sel_hi:[1,0]
	v_pk_add_f32 v[244:245], v[244:245], 1.0 op_sel_hi:[1,0]
	v_pk_add_f32 v[246:247], v[246:247], 1.0 op_sel_hi:[1,0]
	v_rcp_f32_e32 v240, v240
	v_rcp_f32_e32 v241, v241
	v_rcp_f32_e32 v242, v242
	v_rcp_f32_e32 v243, v243
	v_rcp_f32_e32 v244, v244
	v_rcp_f32_e32 v245, v245
	v_rcp_f32_e32 v246, v246
	v_rcp_f32_e32 v247, v247
	s_nop 0
	v_pk_mul_f32 v[224:225], v[224:225], v[240:241]
	v_pk_mul_f32 v[226:227], v[226:227], v[242:243]
	v_pk_mul_f32 v[228:229], v[228:229], v[244:245]
	v_pk_mul_f32 v[230:231], v[230:231], v[246:247]
	v_cvt_pk_bf16_f32 v129, v224, v225
	v_cvt_pk_bf16_f32 v133, v226, v227
	v_cvt_pk_bf16_f32 v137, v228, v229
	v_cvt_pk_bf16_f32 v141, v230, v231
	global_load_dwordx4 v[190:193], v172, s[64:65] offset:192
	global_load_dwordx4 v[194:197], v172, s[64:65] offset:208
	global_load_dwordx4 v[198:201], v172, s[64:65] offset:224
	global_load_dwordx4 v[202:205], v172, s[64:65] offset:240
	s_waitcnt vmcnt(4)
;     __device__ __forceinline__ void operator()(const f32x4 (&acc)[2][2][4][2], const Unit& u, int wr, int wc, int fr, int fq) const {
;     ...
;                     const int cidx = (4 * n + 2 * jp) * 2;
;                     const f32x4 c0a = ct[cidx], c0b = ct[cidx + 1], c1a = ct[cidx + 2], c1b = ct[cidx + 3];
;                     const f32x2 wv0 = {c0a[0], c1a[0]}, wv1 = {c0a[1], c1a[1]}, wv2 = {c0a[2], c1a[2]}, bv = {c0a[3], c1a[3]};
;                     const f32x2 wg0 = {c0b[0], c1b[0]}, wg1 = {c0b[1], c1b[1]}, wg2 = {c0b[2], c1b[2]}, bg = {c0b[3], c1b[3]};
;                     f32x2 uv[4], ug[4], cv[4];
; #pragma unroll
;                     for (int m = 0; m < 4; ++m) { uv[m] = (f32x2){acc[ai][0][m][n][2 * jp], acc[ai][0][m][n][2 * jp + 1]}; ug[m] = (f32x2){acc[ai][1][m][n][2 * jp], acc[ai][1][m][n][2 * jp + 1]}; }
;                     asm volatile("" : "+v"(uv[0]), "+v"(uv[1]), "+v"(uv[2]), "+v"(uv[3]), "+v"(ug[0]), "+v"(ug[1]), "+v"(ug[2]), "+v"(ug[3]));
;                     {
;                         f32x2 rv[4], lv[4];
; #pragma unroll
;                         for (int m = 0; m < 4; ++m) { uv[m] = uv[m] * rs[m]; rv[m] = (f32x2){dpp_ror1(uv[m][0]), dpp_ror1(uv[m][1])}; lv[m] = (f32x2){dpp_ror15(uv[m][0]), dpp_ror15(uv[m][1])}; }
; #pragma unroll
;                         for (int m = 0; m < 4; ++m) { const f32x2 pv_ = (m > 0 && f0) ? rv[m > 0 ? m - 1 : 0] : rv[m], nv_ = (m < 3 && f15) ? lv[m < 3 ? m + 1 : 3] : lv[m];
;                             cv[m] = bv + wv0 * pv_ + wv1 * uv[m] + wv2 * nv_; }
;                     }
;                     asm volatile("" : "+v"(cv[0]), "+v"(cv[1]), "+v"(cv[2]), "+v"(cv[3]));
;                     {
;                         f32x2 rg[4], lg[4];
; #pragma unroll
;                         for (int m = 0; m < 4; ++m) { ug[m] = ug[m] * rs[m]; rg[m] = (f32x2){dpp_ror1(ug[m][0]), dpp_ror1(ug[m][1])}; lg[m] = (f32x2){dpp_ror15(ug[m][0]), dpp_ror15(ug[m][1])}; }
; #pragma unroll
;                         for (int m = 0; m < 4; ++m) { const f32x2 pg_ = (m > 0 && f0) ? rg[m > 0 ? m - 1 : 0] : rg[m], ng_ = (m < 3 && f15) ? lg[m < 3 ? m + 1 : 3] : lg[m];
;                             const f32x2 cgt = bg + wg0 * pg_ + wg1 * ug[m] + wg2 * ng_;
;                             const f32x2 e = cgt * (-LOG2E);
;                             const f32x2 d = (f32x2){__builtin_amdgcn_exp2f(e[0]), __builtin_amdgcn_exp2f(e[1])} + 1.f;
	v_pk_mul_f32 v[28:29], v[28:29], v[178:179] op_sel_hi:[1,0]
	v_pk_mul_f32 v[24:25], v[24:25], v[180:181] op_sel_hi:[1,0]
	v_pk_mul_f32 v[20:21], v[20:21], v[182:183] op_sel_hi:[1,0]
	v_pk_mul_f32 v[16:17], v[16:17], v[144:145] op_sel_hi:[1,0]
	v_pk_mul_f32 v[12:13], v[12:13], v[178:179] op_sel_hi:[1,0]
	v_pk_mul_f32 v[8:9], v[8:9], v[180:181] op_sel_hi:[1,0]
	v_pk_mul_f32 v[4:5], v[4:5], v[182:183] op_sel_hi:[1,0]
	v_pk_mul_f32 v[0:1], v[0:1], v[144:145] op_sel_hi:[1,0]
	s_nop 1
	v_mov_b32_dpp v248, v16 row_shr:1 row_mask:0xf bank_mask:0xf bound_ctrl:1
	v_mov_b32_dpp v249, v17 row_shr:1 row_mask:0xf bank_mask:0xf bound_ctrl:1
	v_mov_b32_dpp v250, v28 row_shl:1 row_mask:0xf bank_mask:0xf bound_ctrl:1
	v_mov_b32_dpp v251, v29 row_shl:1 row_mask:0xf bank_mask:0xf bound_ctrl:1
	v_pk_fma_f32 v[224:225], v[206:207], v[248:249], v[212:213]
	v_pk_fma_f32 v[226:227], v[206:207], v[28:29], v[212:213]
	v_pk_fma_f32 v[228:229], v[206:207], v[24:25], v[212:213]
	v_pk_fma_f32 v[230:231], v[206:207], v[20:21], v[212:213]
	v_pk_fma_f32 v[224:225], v[208:209], v[28:29], v[224:225]
	v_pk_fma_f32 v[226:227], v[208:209], v[24:25], v[226:227]
	v_pk_fma_f32 v[228:229], v[208:209], v[20:21], v[228:229]
	v_pk_fma_f32 v[230:231], v[208:209], v[16:17], v[230:231]
	v_pk_fma_f32 v[224:225], v[210:211], v[24:25], v[224:225]
	v_pk_fma_f32 v[226:227], v[210:211], v[20:21], v[226:227]
	v_pk_fma_f32 v[228:229], v[210:211], v[16:17], v[228:229]
	v_pk_fma_f32 v[230:231], v[210:211], v[250:251], v[230:231]
	s_nop 1
	v_mov_b32_dpp v248, v0 row_shr:1 row_mask:0xf bank_mask:0xf bound_ctrl:1
	v_mov_b32_dpp v249, v1 row_shr:1 row_mask:0xf bank_mask:0xf bound_ctrl:1
	v_mov_b32_dpp v250, v12 row_shl:1 row_mask:0xf bank_mask:0xf bound_ctrl:1
	v_mov_b32_dpp v251, v13 row_shl:1 row_mask:0xf bank_mask:0xf bound_ctrl:1
	v_pk_fma_f32 v[232:233], v[214:215], v[248:249], v[220:221]
	v_pk_fma_f32 v[234:235], v[214:215], v[12:13], v[220:221]
	v_pk_fma_f32 v[236:237], v[214:215], v[8:9], v[220:221]
	v_pk_fma_f32 v[238:239], v[214:215], v[4:5], v[220:221]
	v_pk_fma_f32 v[232:233], v[216:217], v[12:13], v[232:233]
	v_pk_fma_f32 v[234:235], v[216:217], v[8:9], v[234:235]
	v_pk_fma_f32 v[236:237], v[216:217], v[4:5], v[236:237]
	v_pk_fma_f32 v[238:239], v[216:217], v[0:1], v[238:239]
	v_pk_fma_f32 v[232:233], v[218:219], v[8:9], v[232:233]
	v_pk_fma_f32 v[234:235], v[218:219], v[4:5], v[234:235]
	v_pk_fma_f32 v[236:237], v[218:219], v[0:1], v[236:237]
	v_pk_fma_f32 v[238:239], v[218:219], v[250:251], v[238:239]
	v_exp_f32_e64 v240, -v232
	v_exp_f32_e64 v241, -v233
	v_exp_f32_e64 v242, -v234
	v_exp_f32_e64 v243, -v235
	v_exp_f32_e64 v244, -v236
	v_exp_f32_e64 v245, -v237
	v_exp_f32_e64 v246, -v238
	v_exp_f32_e64 v247, -v239
	v_pk_mul_f32 v[224:225], v[224:225], v[232:233]
	v_pk_mul_f32 v[226:227], v[226:227], v[234:235]
	v_pk_mul_f32 v[228:229], v[228:229], v[236:237]
	v_pk_mul_f32 v[230:231], v[230:231], v[238:239]
	v_pk_add_f32 v[240:241], v[240:241], 1.0 op_sel_hi:[1,0]
	v_pk_add_f32 v[242:243], v[242:243], 1.0 op_sel_hi:[1,0]
	v_pk_add_f32 v[244:245], v[244:245], 1.0 op_sel_hi:[1,0]
	v_pk_add_f32 v[246:247], v[246:247], 1.0 op_sel_hi:[1,0]
	v_rcp_f32_e32 v240, v240
	v_rcp_f32_e32 v241, v241
	v_rcp_f32_e32 v242, v242
	v_rcp_f32_e32 v243, v243
	v_rcp_f32_e32 v244, v244
	v_rcp_f32_e32 v245, v245
	v_rcp_f32_e32 v246, v246
	v_rcp_f32_e32 v247, v247
	s_nop 0
	v_pk_mul_f32 v[224:225], v[224:225], v[240:241]
	v_pk_mul_f32 v[226:227], v[226:227], v[242:243]
	v_pk_mul_f32 v[228:229], v[228:229], v[244:245]
	v_pk_mul_f32 v[230:231], v[230:231], v[246:247]
	v_cvt_pk_bf16_f32 v130, v224, v225
	v_cvt_pk_bf16_f32 v134, v226, v227
	v_cvt_pk_bf16_f32 v138, v228, v229
	v_cvt_pk_bf16_f32 v142, v230, v231
	s_waitcnt vmcnt(0)
; __device__ __forceinline__ unsigned cvtpk(float lo, float hi) { f32x2 v = {lo, hi}; bf16x2_t b = __builtin_convertvector(v, bf16x2_t); return __builtin_bit_cast(unsigned, b); }
; __device__ __forceinline__ float dpp_ror1(float x) { return __builtin_bit_cast(float, __builtin_amdgcn_mov_dpp(__builtin_bit_cast(int, x), 0x121, 0xF, 0xF, true)); }
; __device__ __forceinline__ float dpp_ror15(float x) { return __builtin_bit_cast(float, __builtin_amdgcn_mov_dpp(__builtin_bit_cast(int, x), 0x12F, 0xF, 0xF, true)); }
;     __device__ __forceinline__ void operator()(const f32x4 (&acc)[2][2][4][2], const Unit& u, int wr, int wc, int fr, int fq) const {
;     ...
;                         for (int m = 0; m < 4; ++m) { ug[m] = ug[m] * rs[m]; rg[m] = (f32x2){dpp_ror1(ug[m][0]), dpp_ror1(ug[m][1])}; lg[m] = (f32x2){dpp_ror15(ug[m][0]), dpp_ror15(ug[m][1])}; }
; #pragma unroll
;                         for (int m = 0; m < 4; ++m) { const f32x2 pg_ = (m > 0 && f0) ? rg[m > 0 ? m - 1 : 0] : rg[m], ng_ = (m < 3 && f15) ? lg[m < 3 ? m + 1 : 3] : lg[m];
;                             const f32x2 cgt = bg + wg0 * pg_ + wg1 * ug[m] + wg2 * ng_;
;                             const f32x2 e = cgt * (-LOG2E);
;                             const f32x2 d = (f32x2){__builtin_amdgcn_exp2f(e[0]), __builtin_amdgcn_exp2f(e[1])} + 1.f;
;                             const f32x2 sg = {__builtin_amdgcn_rcpf(d[0]), __builtin_amdgcn_rcpf(d[1])};
;                             const f32x2 ov = cv[m] * cgt * sg;
;                             outw[m][n][jp] = cvtpk(ov[0], ov[1]); }
;                     }
;                     asm volatile("" : "+v"(outw[0][n][jp]), "+v"(outw[1][n][jp]), "+v"(outw[2][n][jp]), "+v"(outw[3][n][jp]) :: "memory"); __builtin_amdgcn_sched_barrier(0);
;                 }
; #pragma unroll
;             for (int m = 0; m < 4; ++m) { const int i = 16 * m + fr, t = tbase + i;
;                 if (i >= 1 && i <= 62 && t < slen) { u32x4 w; w.x = outw[m][0][0]; w.y = outw[m][0][1]; w.z = outw[m][1][0]; w.w = outw[m][1][1];
;                     *(u32x4*)(Gout + (size_t)(seqbase + t) * DFF + 128 * u.pn + 32 * wc + 8 * fq) = w; } }
	v_pk_mul_f32 v[30:31], v[30:31], v[178:179] op_sel_hi:[1,0]
	v_pk_mul_f32 v[26:27], v[26:27], v[180:181] op_sel_hi:[1,0]
	v_pk_mul_f32 v[22:23], v[22:23], v[182:183] op_sel_hi:[1,0]
	v_pk_mul_f32 v[18:19], v[18:19], v[144:145] op_sel_hi:[1,0]
	v_pk_mul_f32 v[14:15], v[14:15], v[178:179] op_sel_hi:[1,0]
	v_pk_mul_f32 v[10:11], v[10:11], v[180:181] op_sel_hi:[1,0]
	v_pk_mul_f32 v[6:7], v[6:7], v[182:183] op_sel_hi:[1,0]
	v_pk_mul_f32 v[2:3], v[2:3], v[144:145] op_sel_hi:[1,0]
	s_nop 1
	v_mov_b32_dpp v248, v18 row_shr:1 row_mask:0xf bank_mask:0xf bound_ctrl:1
	v_mov_b32_dpp v249, v19 row_shr:1 row_mask:0xf bank_mask:0xf bound_ctrl:1
	v_mov_b32_dpp v250, v30 row_shl:1 row_mask:0xf bank_mask:0xf bound_ctrl:1
	v_mov_b32_dpp v251, v31 row_shl:1 row_mask:0xf bank_mask:0xf bound_ctrl:1
	v_pk_fma_f32 v[224:225], v[190:191], v[248:249], v[196:197]
	v_pk_fma_f32 v[226:227], v[190:191], v[30:31], v[196:197]
	v_pk_fma_f32 v[228:229], v[190:191], v[26:27], v[196:197]
	v_pk_fma_f32 v[230:231], v[190:191], v[22:23], v[196:197]
	v_pk_fma_f32 v[224:225], v[192:193], v[30:31], v[224:225]
	v_pk_fma_f32 v[226:227], v[192:193], v[26:27], v[226:227]
	v_pk_fma_f32 v[228:229], v[192:193], v[22:23], v[228:229]
	v_pk_fma_f32 v[230:231], v[192:193], v[18:19], v[230:231]
	v_pk_fma_f32 v[224:225], v[194:195], v[26:27], v[224:225]
	v_pk_fma_f32 v[226:227], v[194:195], v[22:23], v[226:227]
	v_pk_fma_f32 v[228:229], v[194:195], v[18:19], v[228:229]
	v_pk_fma_f32 v[230:231], v[194:195], v[250:251], v[230:231]
	s_nop 1
	v_mov_b32_dpp v248, v2 row_shr:1 row_mask:0xf bank_mask:0xf bound_ctrl:1
	v_mov_b32_dpp v249, v3 row_shr:1 row_mask:0xf bank_mask:0xf bound_ctrl:1
	v_mov_b32_dpp v250, v14 row_shl:1 row_mask:0xf bank_mask:0xf bound_ctrl:1
	v_mov_b32_dpp v251, v15 row_shl:1 row_mask:0xf bank_mask:0xf bound_ctrl:1
	v_pk_fma_f32 v[232:233], v[198:199], v[248:249], v[204:205]
	v_pk_fma_f32 v[234:235], v[198:199], v[14:15], v[204:205]
	v_pk_fma_f32 v[236:237], v[198:199], v[10:11], v[204:205]
	v_pk_fma_f32 v[238:239], v[198:199], v[6:7], v[204:205]
	v_pk_fma_f32 v[232:233], v[200:201], v[14:15], v[232:233]
	v_pk_fma_f32 v[234:235], v[200:201], v[10:11], v[234:235]
	v_pk_fma_f32 v[236:237], v[200:201], v[6:7], v[236:237]
	v_pk_fma_f32 v[238:239], v[200:201], v[2:3], v[238:239]
	v_pk_fma_f32 v[232:233], v[202:203], v[10:11], v[232:233]
	v_pk_fma_f32 v[234:235], v[202:203], v[6:7], v[234:235]
	v_pk_fma_f32 v[236:237], v[202:203], v[2:3], v[236:237]
	v_pk_fma_f32 v[238:239], v[202:203], v[250:251], v[238:239]
	v_exp_f32_e64 v240, -v232
	v_exp_f32_e64 v241, -v233
	v_exp_f32_e64 v242, -v234
	v_exp_f32_e64 v243, -v235
	v_exp_f32_e64 v244, -v236
	v_exp_f32_e64 v245, -v237
	v_exp_f32_e64 v246, -v238
	v_exp_f32_e64 v247, -v239
	v_pk_mul_f32 v[224:225], v[224:225], v[232:233]
	v_pk_mul_f32 v[226:227], v[226:227], v[234:235]
	v_pk_mul_f32 v[228:229], v[228:229], v[236:237]
	v_pk_mul_f32 v[230:231], v[230:231], v[238:239]
	v_pk_add_f32 v[240:241], v[240:241], 1.0 op_sel_hi:[1,0]
	v_pk_add_f32 v[242:243], v[242:243], 1.0 op_sel_hi:[1,0]
	v_pk_add_f32 v[244:245], v[244:245], 1.0 op_sel_hi:[1,0]
	v_pk_add_f32 v[246:247], v[246:247], 1.0 op_sel_hi:[1,0]
	v_rcp_f32_e32 v240, v240
	v_rcp_f32_e32 v241, v241
	v_rcp_f32_e32 v242, v242
	v_rcp_f32_e32 v243, v243
	v_rcp_f32_e32 v244, v244
	v_rcp_f32_e32 v245, v245
	v_rcp_f32_e32 v246, v246
	v_rcp_f32_e32 v247, v247
	s_nop 0
	v_pk_mul_f32 v[224:225], v[224:225], v[240:241]
	v_pk_mul_f32 v[226:227], v[226:227], v[242:243]
	v_pk_mul_f32 v[228:229], v[228:229], v[244:245]
	v_pk_mul_f32 v[230:231], v[230:231], v[246:247]
	v_cvt_pk_bf16_f32 v131, v224, v225
	v_cvt_pk_bf16_f32 v135, v226, v227
	v_cvt_pk_bf16_f32 v139, v228, v229
	v_cvt_pk_bf16_f32 v143, v230, v231
	s_sub_i32 s51, s91, s89
	s_sub_i32 s66, s51, 4
	s_max_i32 s66, s66, 0
	v_add_u32_e32 v176, -4, v164
	v_cmp_gt_u32_e32 vcc, s66, v176
	v_add_u32_e32 v176, 0, v174
	v_add_u32_e32 v176, s88, v176
	v_mad_u32_u24 v248, v176, s54, v165
	s_mov_b64 exec, vcc
	global_store_dwordx4 v248, v[128:131], s[86:87]
	s_mov_b64 exec, -1
	s_sub_i32 s66, s51, 1
	s_max_i32 s66, s66, 0
	v_cmp_gt_u32_e32 vcc, s66, v164
	v_add_u32_e32 v176, 1, v174
	v_add_u32_e32 v176, s88, v176
	v_mad_u32_u24 v249, v176, s54, v165
	s_mov_b64 exec, vcc
	global_store_dwordx4 v249, v[132:135], s[86:87]
	s_mov_b64 exec, -1
	s_sub_i32 s66, s51, 2
	s_max_i32 s66, s66, 0
	v_cmp_gt_u32_e32 vcc, s66, v164
	v_add_u32_e32 v176, 2, v174
	v_add_u32_e32 v176, s88, v176
	v_mad_u32_u24 v250, v176, s54, v165
	s_mov_b64 exec, vcc
	global_store_dwordx4 v250, v[136:139], s[86:87]
	s_mov_b64 exec, -1
	s_sub_i32 s66, s51, 3
	s_min_i32 s66, s66, 60
	s_max_i32 s66, s66, 0
	v_cmp_gt_u32_e32 vcc, s66, v164
	v_add_u32_e32 v176, 3, v174
	v_add_u32_e32 v176, s88, v176
	v_mad_u32_u24 v251, v176, s54, v165
	s_mov_b64 exec, vcc
	global_store_dwordx4 v251, v[140:143], s[86:87]
	s_mov_b64 exec, -1
	s_mov_b64 s[2:3], exec
